# v32 + sample chunk loop row loads: -8-row index adjust of the new-window source folded into per-unit biased bases (2 VALU fewer per row, 6 rows per chunk)
# baseline (speedup 1.0000x reference)
.LBB0_1283:
	v_lshlrev_b32_e32 v246, 5, v141
	v_sub_u32_e32 v246, 0, v246
	v_ashrrev_i32_e32 v247, 31, v246
	v_lshl_add_u64 v[242:243], v[144:145], 0, v[246:247]
	v_lshl_add_u64 v[244:245], v[146:147], 0, v[246:247]
	v_lshlrev_b32_e32 v120, 11, v140
	v_lshl_add_u64 v[2:3], s[60:61], 0, v[120:121]
	v_mov_b32_e32 v143, v121
	v_lshl_add_u64 v[2:3], v[142:143], 1, v[2:3]
	v_lshlrev_b32_e32 v120, 1, v122
	v_lshl_add_u64 v[2:3], v[2:3], 0, v[120:121]
	v_add_u32_e32 v1, v179, v155
	global_load_dwordx4 v[56:59], v[2:3], off
	global_load_dwordx4 v[60:63], v[2:3], off offset:32
	global_load_dwordx4 v[52:55], v[2:3], off offset:64
	global_load_dwordx4 v[48:51], v[2:3], off offset:96
	v_min_i32_e32 v2, s53, v1
	v_mul_u32_u24_e32 v2, v2, v177
	v_add_u32_e32 v2, v2, v178
	v_add_u32_e32 v3, -8, v2
	v_cmp_lt_i32_e32 vcc, v2, v180
	v_cmp_ne_u32_e64 s[10:11], 0, v0
	v_cmp_eq_u32_e64 s[80:81], 1, v0
	v_cndmask_b32_e32 v2, v3, v2, vcc
	v_mul_u32_u24_e32 v2, v2, v141
	v_mov_b32_e32 v3, 0
	v_or_b32_e32 v2, v2, v130
	v_cndmask_b32_e32 v5, v145, v149, vcc
	v_cndmask_b32_e32 v4, v144, v148, vcc
	v_lshlrev_b32_e32 v2, 2, v2
	v_lshl_add_u64 v[4:5], v[4:5], 0, v[2:3]
	global_load_dwordx4 v[112:115], v[4:5], off
	v_cndmask_b32_e32 v5, v147, v151, vcc
	v_cndmask_b32_e32 v4, v146, v150, vcc
	v_lshl_add_u64 v[2:3], v[4:5], 0, v[2:3]
	global_load_dwordx4 v[116:119], v[2:3], off
	v_add_u32_e32 v2, 4, v1
	v_min_i32_e32 v2, s53, v2
	v_mul_u32_u24_e32 v2, v2, v177
	v_add_u32_e32 v2, v2, v178
	v_add_u32_e32 v3, -8, v2
	v_cmp_lt_i32_e32 vcc, v2, v180
	v_mul_u32_u24_e32 v199, v177, v1
	s_lshl_b32 s51, s18, 5
	v_cndmask_b32_e32 v2, v3, v2, vcc
	v_mul_u32_u24_e32 v2, v2, v141
	v_mov_b32_e32 v3, 0
	v_or_b32_e32 v2, v2, v130
	v_cndmask_b32_e32 v5, v145, v149, vcc
	v_cndmask_b32_e32 v4, v144, v148, vcc
	v_lshlrev_b32_e32 v2, 2, v2
	v_lshl_add_u64 v[4:5], v[4:5], 0, v[2:3]
	global_load_dwordx4 v[104:107], v[4:5], off
	v_cndmask_b32_e32 v5, v147, v151, vcc
	v_cndmask_b32_e32 v4, v146, v150, vcc
	v_lshl_add_u64 v[2:3], v[4:5], 0, v[2:3]
	global_load_dwordx4 v[108:111], v[2:3], off
	v_add_u32_e32 v2, 8, v1
	v_min_i32_e32 v2, s53, v2
	v_mul_u32_u24_e32 v2, v2, v177
	v_add_u32_e32 v2, v2, v178
	v_add_u32_e32 v3, -8, v2
	v_cmp_lt_i32_e32 vcc, v2, v180
	v_lshlrev_b32_e32 v185, 5, v177
	v_mov_b32_e32 v202, 0
	v_cndmask_b32_e32 v2, v3, v2, vcc
	v_mul_u32_u24_e32 v2, v2, v141
	v_mov_b32_e32 v3, 0
	v_or_b32_e32 v2, v2, v130
	v_cndmask_b32_e32 v5, v145, v149, vcc
	v_cndmask_b32_e32 v4, v144, v148, vcc
	v_lshlrev_b32_e32 v2, 2, v2
	v_lshl_add_u64 v[4:5], v[4:5], 0, v[2:3]
	global_load_dwordx4 v[96:99], v[4:5], off
	v_cndmask_b32_e32 v5, v147, v151, vcc
	v_cndmask_b32_e32 v4, v146, v150, vcc
	v_lshl_add_u64 v[2:3], v[4:5], 0, v[2:3]
	global_load_dwordx4 v[100:103], v[2:3], off
	v_add_u32_e32 v2, 12, v1
	v_min_i32_e32 v2, s53, v2
	v_mul_u32_u24_e32 v2, v2, v177
	v_add_u32_e32 v2, v2, v178
	v_add_u32_e32 v3, -8, v2
	v_cmp_lt_i32_e32 vcc, v2, v180
	s_mov_b32 s33, 0
	s_add_i32 s48, s53, -4
	v_cndmask_b32_e32 v2, v3, v2, vcc
	v_mul_u32_u24_e32 v2, v2, v141
	v_mov_b32_e32 v3, 0
	v_or_b32_e32 v2, v2, v130
	v_cndmask_b32_e32 v5, v145, v149, vcc
	v_cndmask_b32_e32 v4, v144, v148, vcc
	v_lshlrev_b32_e32 v2, 2, v2
	v_lshl_add_u64 v[4:5], v[4:5], 0, v[2:3]
	global_load_dwordx4 v[88:91], v[4:5], off
	v_cndmask_b32_e32 v5, v147, v151, vcc
	v_cndmask_b32_e32 v4, v146, v150, vcc
	v_lshl_add_u64 v[2:3], v[4:5], 0, v[2:3]
	global_load_dwordx4 v[92:95], v[2:3], off
	v_add_u32_e32 v2, 16, v1
	v_min_i32_e32 v2, s53, v2
	v_mul_u32_u24_e32 v2, v2, v177
	v_add_u32_e32 v2, v2, v178
	v_add_u32_e32 v3, -8, v2
	v_cmp_lt_i32_e32 vcc, v2, v180
	s_add_i32 s49, s53, -8
	s_add_i32 s56, s53, -12
	v_cndmask_b32_e32 v2, v3, v2, vcc
	v_mul_u32_u24_e32 v2, v2, v141
	v_mov_b32_e32 v3, 0
	v_or_b32_e32 v2, v2, v130
	v_cndmask_b32_e32 v5, v145, v149, vcc
	v_cndmask_b32_e32 v4, v144, v148, vcc
	v_lshlrev_b32_e32 v2, 2, v2
	v_lshl_add_u64 v[4:5], v[4:5], 0, v[2:3]
	global_load_dwordx4 v[80:83], v[4:5], off
	v_cndmask_b32_e32 v5, v147, v151, vcc
	v_cndmask_b32_e32 v4, v146, v150, vcc
	v_lshl_add_u64 v[2:3], v[4:5], 0, v[2:3]
	global_load_dwordx4 v[84:87], v[2:3], off
	v_add_u32_e32 v2, 20, v1
	v_min_i32_e32 v2, s53, v2
	v_mul_u32_u24_e32 v2, v2, v177
	v_add_u32_e32 v2, v2, v178
	v_add_u32_e32 v3, -8, v2
	v_cmp_lt_i32_e32 vcc, v2, v180
	s_add_i32 s42, s53, -16
	s_sub_i32 s54, s53, 20
	v_cndmask_b32_e32 v2, v3, v2, vcc
	v_mul_u32_u24_e32 v2, v2, v141
	v_mov_b32_e32 v3, 0
	v_or_b32_e32 v2, v2, v130
	v_cndmask_b32_e32 v5, v145, v149, vcc
	v_cndmask_b32_e32 v4, v144, v148, vcc
	v_lshlrev_b32_e32 v2, 2, v2
	v_lshl_add_u64 v[4:5], v[4:5], 0, v[2:3]
	global_load_dwordx4 v[64:67], v[4:5], off
	v_cndmask_b32_e32 v5, v147, v151, vcc
	v_cndmask_b32_e32 v4, v146, v150, vcc
	v_lshl_add_u64 v[2:3], v[4:5], 0, v[2:3]
	global_load_dwordx4 v[68:71], v[2:3], off
	v_add_u32_e32 v2, 24, v1
	v_min_i32_e32 v2, s53, v2
	v_mul_u32_u24_e32 v2, v2, v177
	v_add_u32_e32 v2, v2, v178
	v_add_u32_e32 v3, -8, v2
	v_cmp_lt_i32_e32 vcc, v2, v180
	s_sub_i32 s50, s53, 24
	s_sub_i32 s34, s53, 28
	v_cndmask_b32_e32 v2, v3, v2, vcc
	v_mul_u32_u24_e32 v2, v2, v141
	v_mov_b32_e32 v3, 0
	v_or_b32_e32 v2, v2, v130
	v_cndmask_b32_e32 v5, v145, v149, vcc
	v_cndmask_b32_e32 v4, v144, v148, vcc
	v_lshlrev_b32_e32 v2, 2, v2
	v_lshl_add_u64 v[4:5], v[4:5], 0, v[2:3]
	global_load_dwordx4 v[72:75], v[4:5], off
	v_cndmask_b32_e32 v5, v147, v151, vcc
	v_cndmask_b32_e32 v4, v146, v150, vcc
	v_lshl_add_u64 v[2:3], v[4:5], 0, v[2:3]
	global_load_dwordx4 v[76:79], v[2:3], off
	v_add_u32_e32 v2, 28, v1
	v_min_i32_e32 v2, s53, v2
	v_mul_u32_u24_e32 v2, v2, v177
	v_add_u32_e32 v2, v2, v178
	v_add_u32_e32 v3, -8, v2
	v_cmp_lt_i32_e32 vcc, v2, v180
	s_add_i32 s18, s51, 32
	v_add_u32_e32 v182, v159, v179
	v_cndmask_b32_e32 v2, v3, v2, vcc
	v_mul_u32_u24_e32 v2, v2, v141
	v_mov_b32_e32 v3, 0
	v_or_b32_e32 v2, v2, v130
	v_cndmask_b32_e32 v5, v145, v149, vcc
	v_cndmask_b32_e32 v4, v144, v148, vcc
	v_lshlrev_b32_e32 v2, 2, v2
	v_lshl_add_u64 v[4:5], v[4:5], 0, v[2:3]
	global_load_dwordx4 v[32:35], v[4:5], off
	v_cndmask_b32_e32 v5, v147, v151, vcc
	v_cndmask_b32_e32 v4, v146, v150, vcc
	v_lshl_add_u64 v[2:3], v[4:5], 0, v[2:3]
	global_load_dwordx4 v[36:39], v[2:3], off
	v_and_b32_e32 v3, 64, v128
	v_xor_b32_e32 v2, 32, v128
	v_add_u32_e32 v3, 64, v3
	v_cmp_lt_i32_e32 vcc, v2, v3
	v_cmp_ne_u32_e64 s[8:9], 1, v0
	v_add_u32_e32 v0, v158, v139
	v_cndmask_b32_e32 v2, v128, v2, vcc
	v_lshlrev_b32_e32 v143, 2, v2
	v_add_u32_e32 v2, v160, v179
	v_sub_u32_e32 v181, v0, v179
	v_add_u32_e32 v0, -8, v178
	v_mul_lo_u32 v183, v177, v2
	v_add_u32_e32 v2, v0, v183
	v_mul_lo_u32 v184, v141, v2
	v_add_u32_e32 v2, v161, v179
	v_mul_lo_u32 v187, v177, v2
	v_add_u32_e32 v2, v0, v187
	v_mul_lo_u32 v188, v141, v2
	v_add_u32_e32 v2, v162, v179
	v_mul_lo_u32 v189, v177, v2
	v_add_u32_e32 v2, v0, v189
	v_mul_lo_u32 v190, v141, v2
	v_add_u32_e32 v2, v163, v179
	v_mul_lo_u32 v191, v177, v2
	v_add_u32_e32 v2, v0, v191
	v_mul_lo_u32 v192, v141, v2
	v_add_u32_e32 v2, v167, v179
	v_mul_lo_u32 v193, v177, v2
	v_add_u32_e32 v2, v0, v193
	v_mul_lo_u32 v194, v141, v2
	v_add_u32_e32 v2, v168, v179
	v_mul_lo_u32 v195, v177, v2
	v_add_u32_e32 v2, v0, v195
	v_mul_lo_u32 v196, v141, v2
	v_add_u32_e32 v2, v169, v179
	v_mul_lo_u32 v197, v177, v2
	v_add_u32_e32 v2, v0, v197
	v_add_u32_e32 v0, v0, v199
	v_mul_lo_u32 v186, v185, v141
	v_mul_lo_u32 v198, v141, v2
	v_mul_lo_u32 v200, v141, v0
	v_mov_b32_e32 v208, 0xf149f2ca
	v_mov_b32_e32 v201, v178
	v_mov_b32_e32 v16, 0
	v_mov_b32_e32 v17, v202
	v_mov_b32_e32 v18, v202
	v_mov_b32_e32 v19, v202
	v_mov_b32_e32 v20, v202
	v_mov_b32_e32 v21, v202
	v_mov_b32_e32 v22, v202
	v_mov_b32_e32 v23, v202
	v_mov_b32_e32 v24, v202
	v_mov_b32_e32 v25, v202
	v_mov_b32_e32 v26, v202
	v_mov_b32_e32 v27, v202
	v_mov_b32_e32 v28, v202
	v_mov_b32_e32 v29, v202
	v_mov_b32_e32 v30, v202
	v_mov_b32_e32 v31, v202
	v_mov_b32_e32 v0, 0
	v_mov_b32_e32 v1, v202
	v_mov_b32_e32 v2, v202
	v_mov_b32_e32 v3, v202
	v_mov_b32_e32 v4, v202
	v_mov_b32_e32 v5, v202
	v_mov_b32_e32 v6, v202
	v_mov_b32_e32 v7, v202
	v_mov_b32_e32 v8, v202
	v_mov_b32_e32 v9, v202
	v_mov_b32_e32 v10, v202
	v_mov_b32_e32 v11, v202
	v_mov_b32_e32 v12, v202
	v_mov_b32_e32 v13, v202
	v_mov_b32_e32 v14, v202
	v_mov_b32_e32 v15, v202

.LBB0_1326:
	v_subrev_u32_e32 v32, 28, v182
	v_min_i32_e32 v32, s53, v32
	v_mad_u32_u24 v32, v32, v177, v178
	v_cmp_lt_i32_e32 vcc, v32, v180
	v_add_u32_e32 v211, v127, v129
	ds_read_b128 v[216:219], v211 offset:64
	v_mad_u32_u24 v32, v32, v141, v130
	v_mov_b32_e32 v33, 0
	v_cndmask_b32_e32 v35, v243, v149, vcc
	v_cndmask_b32_e32 v34, v242, v148, vcc
	v_lshl_add_u64 v[34:35], v[32:33], 2, v[34:35]
	global_load_dwordx4 v[112:115], v[34:35], off
	v_cndmask_b32_e32 v35, v245, v151, vcc
	v_cndmask_b32_e32 v34, v244, v150, vcc
	v_lshl_add_u64 v[34:35], v[32:33], 2, v[34:35]
	global_load_dwordx4 v[116:119], v[34:35], off
	v_subrev_u32_e32 v32, 24, v182
	v_min_i32_e32 v32, s53, v32
	v_mad_u32_u24 v32, v32, v177, v178
	v_cmp_lt_i32_e32 vcc, v32, v180
	v_min_i32_e32 v120, s53, v182
	v_mul_u32_u24_e32 v120, v120, v177
	v_mad_u32_u24 v32, v32, v141, v130
	v_cndmask_b32_e32 v35, v243, v149, vcc
	v_cndmask_b32_e32 v34, v242, v148, vcc
	v_lshl_add_u64 v[34:35], v[32:33], 2, v[34:35]
	global_load_dwordx4 v[104:107], v[34:35], off
	v_cndmask_b32_e32 v35, v245, v151, vcc
	v_cndmask_b32_e32 v34, v244, v150, vcc
	v_lshl_add_u64 v[34:35], v[32:33], 2, v[34:35]
	global_load_dwordx4 v[108:111], v[34:35], off
	v_subrev_u32_e32 v32, 20, v182
	v_min_i32_e32 v32, s53, v32
	v_mad_u32_u24 v32, v32, v177, v178
	v_cmp_lt_i32_e32 vcc, v32, v180
	v_add_u32_e32 v120, v120, v178
	v_add_u32_e32 v209, -8, v120
	v_mad_u32_u24 v32, v32, v141, v130
	v_cndmask_b32_e32 v35, v243, v149, vcc
	v_cndmask_b32_e32 v34, v242, v148, vcc
	v_lshl_add_u64 v[34:35], v[32:33], 2, v[34:35]
	global_load_dwordx4 v[96:99], v[34:35], off
	v_cndmask_b32_e32 v35, v245, v151, vcc
	v_cndmask_b32_e32 v34, v244, v150, vcc
	v_lshl_add_u64 v[34:35], v[32:33], 2, v[34:35]
	global_load_dwordx4 v[100:103], v[34:35], off
	v_add_u32_e32 v32, -16, v182
	v_min_i32_e32 v32, s53, v32
	v_mad_u32_u24 v32, v32, v177, v178
	v_cmp_lt_i32_e32 vcc, v32, v180
	v_add_u32_e32 v184, v184, v186
	v_add_u32_e32 v201, v201, v185
	v_mad_u32_u24 v32, v32, v141, v130
	v_cndmask_b32_e32 v35, v243, v149, vcc
	v_cndmask_b32_e32 v34, v242, v148, vcc
	v_lshl_add_u64 v[34:35], v[32:33], 2, v[34:35]
	global_load_dwordx4 v[88:91], v[34:35], off
	v_cndmask_b32_e32 v35, v245, v151, vcc
	v_cndmask_b32_e32 v34, v244, v150, vcc
	v_lshl_add_u64 v[34:35], v[32:33], 2, v[34:35]
	global_load_dwordx4 v[92:95], v[34:35], off
	v_add_u32_e32 v32, -12, v182
	v_min_i32_e32 v32, s53, v32
	v_mad_u32_u24 v32, v32, v177, v178
	v_cmp_lt_i32_e32 vcc, v32, v180
	ds_read_b128 v[212:215], v211 offset:32
	v_add_u32_e32 v188, v188, v186
	v_mad_u32_u24 v32, v32, v141, v130
	v_cndmask_b32_e32 v35, v243, v149, vcc
	v_cndmask_b32_e32 v34, v242, v148, vcc
	v_lshl_add_u64 v[34:35], v[32:33], 2, v[34:35]
	global_load_dwordx4 v[80:83], v[34:35], off
	v_cndmask_b32_e32 v35, v245, v151, vcc
	v_cndmask_b32_e32 v34, v244, v150, vcc
	v_lshl_add_u64 v[34:35], v[32:33], 2, v[34:35]
	global_load_dwordx4 v[84:87], v[34:35], off
	v_add_u32_e32 v32, -8, v182
	v_min_i32_e32 v32, s53, v32
	v_mad_u32_u24 v32, v32, v177, v178
	v_cmp_lt_i32_e32 vcc, v32, v180
	v_add_u32_e32 v190, v190, v186
	v_add_u32_e32 v192, v192, v186
	v_mad_u32_u24 v32, v32, v141, v130
	v_cndmask_b32_e32 v35, v243, v149, vcc
	v_cndmask_b32_e32 v34, v242, v148, vcc
	v_lshl_add_u64 v[34:35], v[32:33], 2, v[34:35]
	global_load_dwordx4 v[64:67], v[34:35], off
	v_cndmask_b32_e32 v35, v245, v151, vcc
	v_cndmask_b32_e32 v34, v244, v150, vcc
	v_lshl_add_u64 v[34:35], v[32:33], 2, v[34:35]
	global_load_dwordx4 v[68:71], v[34:35], off
	v_add_u32_e32 v32, -4, v182
	v_min_i32_e32 v32, s53, v32
	v_mul_u32_u24_e32 v32, v32, v177
	v_add_u32_e32 v32, v32, v178
	v_add_u32_e32 v33, -8, v32
	v_cmp_lt_i32_e32 vcc, v32, v180
	v_add_u32_e32 v182, 32, v182
	v_add_u32_e32 v194, v194, v186
	v_cndmask_b32_e32 v32, v33, v32, vcc
	v_mul_u32_u24_e32 v32, v32, v141
	v_or_b32_e32 v36, v32, v130
	v_mov_b32_e32 v37, 0
	ds_read_b128 v[32:35], v211
	v_cndmask_b32_e32 v39, v145, v149, vcc
	v_cndmask_b32_e32 v38, v144, v148, vcc
	v_lshlrev_b64 v[76:77], 2, v[36:37]
	v_lshl_add_u64 v[36:37], v[38:39], 0, v[76:77]
	global_load_dwordx4 v[72:75], v[36:37], off
	s_waitcnt lgkmcnt(0)
	v_mfma_f32_32x32x16_bf16 v[32:47], v[32:35], v[56:59], 0
	v_cndmask_b32_e32 v79, v147, v151, vcc
	v_cndmask_b32_e32 v78, v146, v150, vcc
	v_cmp_lt_i32_e32 vcc, v120, v180
	v_lshl_add_u64 v[76:77], v[78:79], 0, v[76:77]
	global_load_dwordx4 v[76:79], v[76:77], off
	v_cndmask_b32_e32 v120, v209, v120, vcc
	v_mul_u32_u24_e32 v220, v120, v141
	v_mfma_f32_32x32x16_bf16 v[32:47], v[212:215], v[60:63], v[32:47]
	ds_read_b128 v[212:215], v211 offset:96
	v_add_u32_e32 v196, v196, v186
	v_add_u32_e32 v198, v198, v186
	v_add_u32_e32 v200, v200, v186
	v_mfma_f32_32x32x16_bf16 v[32:47], v[216:219], v[52:55], v[32:47]
	v_add_u32_e32 v120, s33, v181
	v_cmp_le_u32_e64 s[16:17], v120, v135
	v_or_b32_e32 v218, v220, v130
	v_mov_b32_e32 v219, 0
	v_cndmask_b32_e32 v217, v145, v149, vcc
	s_waitcnt lgkmcnt(0)
	v_mfma_f32_32x32x16_bf16 v[32:47], v[212:215], v[48:51], v[32:47]
	v_cndmask_b32_e32 v216, v144, v148, vcc
	v_lshlrev_b64 v[218:219], 2, v[218:219]
	s_sub_i32 s33, s33, 32
	s_nop 8
	v_cndmask_b32_e64 v210, v173, v32, s[16:17]
	v_add_u32_e32 v32, -1, v120
	v_cmp_le_u32_e64 s[16:17], v32, v135
	s_nop 1
	v_cndmask_b32_e64 v212, v173, v33, s[16:17]
	v_add_u32_e32 v33, -2, v120
	v_cmp_le_u32_e64 s[16:17], v33, v135
	v_add_u32_e32 v33, -3, v120
	v_max3_f32 v32, v210, s90, v212
	v_cndmask_b32_e64 v213, v173, v34, s[16:17]
	v_cmp_le_u32_e64 s[16:17], v33, v135
	v_add_u32_e32 v33, -8, v120
	s_nop 0
	v_cndmask_b32_e64 v214, v173, v35, s[16:17]
	v_cmp_le_u32_e64 s[16:17], v33, v135
	v_add_u32_e32 v33, -9, v120
	v_max3_f32 v32, v32, v213, v214
	v_cndmask_b32_e64 v215, v173, v36, s[16:17]
	v_cmp_le_u32_e64 s[16:17], v33, v135
	v_add_u32_e32 v33, -10, v120
	v_cndmask_b32_e32 v36, v146, v150, vcc
	v_cndmask_b32_e64 v220, v173, v37, s[16:17]
	v_cmp_le_u32_e64 s[16:17], v33, v135
	v_add_u32_e32 v33, -11, v120
	v_max3_f32 v32, v32, v215, v220
	v_cndmask_b32_e64 v221, v173, v38, s[16:17]
	v_cmp_le_u32_e64 s[16:17], v33, v135
	v_add_u32_e32 v33, -16, v120
	v_cndmask_b32_e32 v37, v147, v151, vcc
	v_cndmask_b32_e64 v222, v173, v39, s[16:17]
	v_cmp_le_u32_e64 s[16:17], v33, v135
	v_subrev_u32_e32 v33, 17, v120
	v_max3_f32 v32, v32, v221, v222
	v_cndmask_b32_e64 v40, v173, v40, s[16:17]
	v_cmp_le_u32_e64 s[16:17], v33, v135
	v_subrev_u32_e32 v33, 18, v120
	v_lshl_add_u64 v[36:37], v[36:37], 0, v[218:219]
	v_cndmask_b32_e64 v41, v173, v41, s[16:17]
	v_cmp_le_u32_e64 s[16:17], v33, v135
	v_subrev_u32_e32 v33, 19, v120
	v_max3_f32 v32, v32, v40, v41
	v_cndmask_b32_e64 v42, v173, v42, s[16:17]
	v_cmp_le_u32_e64 s[16:17], v33, v135
	v_subrev_u32_e32 v33, 24, v120
	s_nop 0
	v_cndmask_b32_e64 v43, v173, v43, s[16:17]
	v_cmp_le_u32_e64 s[16:17], v33, v135
	v_subrev_u32_e32 v33, 25, v120
	v_max3_f32 v32, v32, v42, v43
	v_cndmask_b32_e64 v44, v173, v44, s[16:17]
	v_cmp_le_u32_e64 s[16:17], v33, v135
	v_subrev_u32_e32 v33, 26, v120
	s_nop 0
	v_cndmask_b32_e64 v45, v173, v45, s[16:17]
	v_cmp_le_u32_e64 s[16:17], v33, v135
	v_subrev_u32_e32 v33, 27, v120
	v_max3_f32 v32, v32, v44, v45
	v_cndmask_b32_e64 v46, v173, v46, s[16:17]
	v_cmp_le_u32_e64 s[16:17], v33, v135
	s_nop 1
	v_cndmask_b32_e64 v47, v173, v47, s[16:17]
	v_max3_f32 v38, v32, v46, v47
	v_mov_b32_e32 v39, v38
	s_nop 1
	v_permlane32_swap_b32_e32 v39, v38
	v_lshl_add_u64 v[32:33], v[216:217], 0, v[218:219]
	global_load_dwordx4 v[32:35], v[32:33], off
	s_add_i32 s16, s18, s33
	s_cmp_lg_u32 s16, 0
	s_waitcnt lgkmcnt(0)
	v_max3_f32 v209, v208, v38, v39
	v_sub_f32_e32 v38, v210, v209
	v_exp_f32_e32 v210, v38
	global_load_dwordx4 v[36:39], v[36:37], off
	v_sub_f32_e32 v212, v212, v209
	v_exp_f32_e32 v212, v212
	v_sub_f32_e32 v213, v213, v209
	v_exp_f32_e32 v213, v213
	v_sub_f32_e32 v214, v214, v209
	v_exp_f32_e32 v214, v214
	v_sub_f32_e32 v215, v215, v209
	v_sub_f32_e32 v120, v208, v209
	v_add_f32_e32 v208, 0, v210
	v_exp_f32_e32 v215, v215
	v_sub_f32_e32 v216, v220, v209
	v_add_f32_e32 v208, v212, v208
	v_exp_f32_e32 v216, v216
	v_sub_f32_e32 v217, v221, v209
	v_add_f32_e32 v208, v213, v208
	v_exp_f32_e32 v217, v217
	v_sub_f32_e32 v218, v222, v209
	v_add_f32_e32 v208, v214, v208
	v_exp_f32_e32 v218, v218
	v_sub_f32_e32 v40, v40, v209
	v_add_f32_e32 v208, v215, v208
	v_exp_f32_e32 v220, v40
	v_sub_f32_e32 v41, v41, v209
	v_add_f32_e32 v40, v216, v208
	v_exp_f32_e32 v208, v41
	v_sub_f32_e32 v41, v42, v209
	v_add_f32_e32 v40, v217, v40
	v_exp_f32_e32 v221, v41
	v_sub_f32_e32 v41, v43, v209
	v_add_f32_e32 v40, v218, v40
	v_exp_f32_e32 v222, v41
	v_sub_f32_e32 v41, v44, v209
	v_add_f32_e32 v40, v220, v40
	v_exp_f32_e32 v223, v41
	v_sub_f32_e32 v41, v45, v209
	v_add_f32_e32 v40, v208, v40
	v_exp_f32_e32 v224, v41
	v_sub_f32_e32 v41, v46, v209
	v_add_f32_e32 v40, v221, v40
	v_exp_f32_e32 v225, v41
	v_sub_f32_e32 v41, v47, v209
	v_add_f32_e32 v40, v222, v40
	v_exp_f32_e32 v226, v41
	v_add_f32_e32 v40, v223, v40
	v_add_f32_e32 v40, v224, v40
	v_add_f32_e32 v40, v225, v40
	v_exp_f32_e32 v120, v120
	v_add_f32_e32 v227, v226, v40
	ds_read_b64_tr_b16 v[40:41], v175 offset:4608
	ds_read_b64_tr_b16 v[42:43], v175 offset:5760
	v_cvt_pk_bf16_f32 v44, v210, v212
	v_cvt_pk_bf16_f32 v45, v213, v214
	v_cvt_pk_bf16_f32 v46, v215, v216
	v_cvt_pk_bf16_f32 v47, v217, v218
	ds_read_b64_tr_b16 v[212:213], v175 offset:6912
	ds_read_b64_tr_b16 v[214:215], v175 offset:8064
	ds_read_b64_tr_b16 v[218:219], v175 offset:5824
	ds_read_b64_tr_b16 v[216:217], v175 offset:4672
	v_mul_f32_e32 v14, v120, v14
	v_mul_f32_e32 v15, v120, v15
	v_mul_f32_e32 v12, v120, v12
	v_mul_f32_e32 v13, v120, v13
	v_mul_f32_e32 v10, v120, v10
	v_mul_f32_e32 v11, v120, v11
	v_mul_f32_e32 v8, v120, v8
	v_mul_f32_e32 v9, v120, v9
	v_mul_f32_e32 v6, v120, v6
	v_mul_f32_e32 v7, v120, v7
	v_mul_f32_e32 v4, v120, v4
	v_mul_f32_e32 v5, v120, v5
	v_mul_f32_e32 v2, v120, v2
	v_mul_f32_e32 v3, v120, v3
	v_mul_f32_e32 v0, v120, v0
	v_mul_f32_e32 v1, v120, v1
	v_mul_f32_e32 v30, v120, v30
	v_mul_f32_e32 v31, v120, v31
	v_mul_f32_e32 v28, v120, v28
	v_mul_f32_e32 v29, v120, v29
	v_mul_f32_e32 v26, v120, v26
	v_mul_f32_e32 v27, v120, v27
	v_mul_f32_e32 v24, v120, v24
	v_mul_f32_e32 v25, v120, v25
	v_mul_f32_e32 v22, v120, v22
	v_mul_f32_e32 v23, v120, v23
	v_mul_f32_e32 v20, v120, v20
	v_mul_f32_e32 v21, v120, v21
	v_mul_f32_e32 v18, v120, v18
	v_mul_f32_e32 v19, v120, v19
	v_mul_f32_e32 v16, v120, v16
	v_mul_f32_e32 v17, v120, v17
	s_waitcnt lgkmcnt(4)
	v_mfma_f32_32x32x16_bf16 v[0:15], v[40:43], v[44:47], v[0:15]
	v_cvt_pk_bf16_f32 v40, v220, v208
	v_cvt_pk_bf16_f32 v41, v221, v222
	v_cvt_pk_bf16_f32 v42, v223, v224
	ds_read_b64_tr_b16 v[222:223], v175 offset:8128
	ds_read_b64_tr_b16 v[220:221], v175 offset:6976
	v_cvt_pk_bf16_f32 v43, v225, v226
	s_waitcnt lgkmcnt(2)
	v_mfma_f32_32x32x16_bf16 v[16:31], v[216:219], v[44:47], v[16:31]
	v_mov_b32_e32 v44, v227
	s_nop 1
	v_permlane32_swap_b32_e32 v44, v227
	s_waitcnt lgkmcnt(0)
	v_add_f32_e32 v210, v227, v44
	v_fmac_f32_e32 v210, v202, v120
	v_mfma_f32_32x32x16_bf16 v[0:15], v[212:215], v[40:43], v[0:15]
	v_mfma_f32_32x32x16_bf16 v[16:31], v[220:223], v[40:43], v[16:31]
	s_cbranch_scc0 .LBB0_1328
	v_mov_b32_e32 v208, v209
	v_mov_b32_e32 v202, v210
	s_branch .LBB0_1284
